# diff attention: half-tile software pipeline (QK of next 32-key half overlaps softmax of current half; K LDS window shifted by 32 keys); rescale check per 32 keys
# speedup vs baseline: 1.0379x; 1.0098x over previous
.LBB0_800:
	s_or_b32 s90, s10, s23
	s_lshl_b64 s[12:13], s[90:91], 1
	v_lshl_add_u64 v[2:3], v[186:187], 0, s[12:13]
	v_mov_b32_e32 v20, v194
	global_load_dwordx4 v[114:117], v[2:3], off
	global_load_dwordx4 v[118:121], v[2:3], off offset:32
	global_load_dwordx4 v[122:125], v[2:3], off offset:64
	global_load_dwordx4 v[126:129], v[2:3], off offset:96
	s_xor_b64 s[8:9], s[8:9], -1
	v_lshrrev_b32_e32 v0, 2, v20
	v_and_b32_e32 v0, 0x3ffffe, v0
	v_lshlrev_b32_e32 v6, 4, v20
	s_add_u32 s12, s25, s12
	v_and_b32_e32 v183, 0x70, v6
	v_mul_u32_u24_e32 v0, 0xc00, v0
	s_addc_u32 s13, s26, s13
	v_or_b32_e32 v0, v0, v183
	v_ashrrev_i32_e32 v21, 3, v20
	v_add_u32_e32 v246, 0x30000, v0
	global_load_dwordx4 v[2:5], v246, s[12:13] offset:2048
	v_and_b32_e32 v205, 0xf0, v6
	v_and_b32_e32 v6, 0x3ffffe, v21
	v_mul_u32_u24_e32 v6, 0xc00, v6
	v_or_b32_e32 v16, v6, v205
	global_load_dwordx4 v[6:9], v16, s[2:3]
	v_add_u32_e32 v18, 0x30000, v16
	global_load_dwordx4 v[10:13], v18, s[2:3]
	s_mov_b32 s100, 0xfffd0000
	s_mov_b32 s101, -1
	v_lshl_add_u64 v[248:249], s[12:13], 0, v[0:1]
	v_lshl_add_u64 v[248:249], v[248:249], 0, s[100:101]
	global_load_dwordx4 v[242:245], v[248:249], off offset:2048
	v_mul_lo_u32 v206, v21, s88
	v_add3_u32 v21, 0, v206, v183
	s_movk_i32 s11, 0x140
	v_lshl_add_u64 v[14:15], s[12:13], 0, v[0:1]
	s_add_i32 s90, s24, s10
	v_mov_b32_e32 v19, v1
	v_mov_b32_e32 v17, v1
	v_lshl_add_u64 v[192:193], s[6:7], 0, v[18:19]
	v_lshl_add_u64 v[190:191], s[6:7], 0, v[16:17]
	v_mov_b32_e32 v212, 0
	s_mov_b32 s29, 0
	v_mov_b32_e32 v66, 0
	v_mov_b32_e32 v67, v212
	v_mov_b32_e32 v68, v212
	v_mov_b32_e32 v69, v212
	v_mov_b32_e32 v70, v212
	v_mov_b32_e32 v71, v212
	v_mov_b32_e32 v72, v212
	v_mov_b32_e32 v73, v212
	v_mov_b32_e32 v74, v212
	v_mov_b32_e32 v75, v212
	v_mov_b32_e32 v76, v212
	v_mov_b32_e32 v77, v212
	v_mov_b32_e32 v78, v212
	v_mov_b32_e32 v79, v212
	v_mov_b32_e32 v80, v212
	v_mov_b32_e32 v81, v212
	s_waitcnt vmcnt(3)
	ds_write_b128 v21, v[2:5]
	v_lshrrev_b32_e32 v2, 4, v20
	v_mul_lo_u32 v207, v2, s11
	v_add3_u32 v2, 0, v205, v207
	s_mov_b32 s11, 0x90000
	s_waitcnt vmcnt(2)
	ds_write_b128 v2, v[6:9] offset:9216
	s_waitcnt vmcnt(1)
	ds_write_b128 v2, v[10:13] offset:19456
	s_waitcnt vmcnt(0)
	ds_write_b128 v21, v[242:245] offset:29696
	v_add_co_u32_e32 v2, vcc, s11, v14
	s_lshl_b64 s[10:11], s[90:91], 1
	s_nop 0
	v_addc_co_u32_e32 v3, vcc, 0, v15, vcc
	global_load_dwordx4 v[130:133], v[2:3], off offset:2048
	global_load_dwordx4 v[134:137], v16, s[4:5]
	global_load_dwordx4 v[138:141], v18, s[4:5]
	v_and_b32_e32 v2, 31, v20
	v_bfe_u32 v3, v20, 5, 1
	v_mul_u32_u24_e32 v208, 0x90, v2
	v_bfe_u32 v2, v20, 2, 2
	v_lshl_or_b32 v2, v3, 2, v2
	v_lshlrev_b32_e32 v209, 4, v3
	v_mul_u32_u24_e32 v210, 0x140, v2
	v_and_b32_e32 v2, 16, v20
	v_lshlrev_b32_e32 v3, 2, v20
	s_add_u32 s10, s27, s10
	v_and_or_b32 v2, v3, 12, v2
	s_addc_u32 s11, s28, s11
	v_mov_b32_e32 v14, v1
	v_mov_b32_e32 v15, v1
	v_lshlrev_b32_e32 v211, 1, v2
	v_lshl_add_u64 v[188:189], s[10:11], 0, v[0:1]
	s_mov_b32 s98, 0x30000
	s_mov_b32 s99, 0
	v_lshl_add_u64 v[188:189], v[188:189], 0, s[98:99]
	v_mov_b32_e32 v0, v1
	v_mov_b32_e32 v2, v1
	v_mov_b32_e32 v3, v1
	v_mov_b32_e32 v4, v1
	v_mov_b32_e32 v5, v1
	v_mov_b32_e32 v6, v1
	v_mov_b32_e32 v7, v1
	v_mov_b32_e32 v8, v1
	v_mov_b32_e32 v9, v1
	v_mov_b32_e32 v10, v1
	v_mov_b32_e32 v11, v1
	v_mov_b32_e32 v12, v1
	v_mov_b32_e32 v13, v1
	v_mov_b64_e32 v[64:65], v[14:15]
	v_mov_b64_e32 v[48:49], v[14:15]
	v_mov_b64_e32 v[32:33], v[14:15]
	v_mov_b64_e32 v[62:63], v[12:13]
	v_mov_b64_e32 v[60:61], v[10:11]
	v_mov_b64_e32 v[58:59], v[8:9]
	v_mov_b64_e32 v[56:57], v[6:7]
	v_mov_b64_e32 v[54:55], v[4:5]
	v_mov_b64_e32 v[52:53], v[2:3]
	v_mov_b64_e32 v[50:51], v[0:1]
	v_mov_b64_e32 v[46:47], v[12:13]
	v_mov_b64_e32 v[44:45], v[10:11]
	v_mov_b64_e32 v[42:43], v[8:9]
	v_mov_b64_e32 v[40:41], v[6:7]
	v_mov_b64_e32 v[38:39], v[4:5]
	v_mov_b64_e32 v[36:37], v[2:3]
	v_mov_b64_e32 v[34:35], v[0:1]
	v_mov_b64_e32 v[30:31], v[12:13]
	v_mov_b64_e32 v[28:29], v[10:11]
	v_mov_b64_e32 v[26:27], v[8:9]
	v_mov_b64_e32 v[24:25], v[6:7]
	v_mov_b64_e32 v[22:23], v[4:5]
	v_mov_b64_e32 v[20:21], v[2:3]
	v_mov_b64_e32 v[18:19], v[0:1]
	v_mov_b64_e32 v[16:17], v[14:15]
	s_mov_b64 s[10:11], 0
	v_mov_b64_e32 v[14:15], v[12:13]
	v_mov_b64_e32 v[12:13], v[10:11]
	v_mov_b64_e32 v[10:11], v[8:9]
	v_mov_b64_e32 v[8:9], v[6:7]
	v_mov_b64_e32 v[6:7], v[4:5]
	v_mov_b64_e32 v[4:5], v[2:3]
	v_mov_b64_e32 v[2:3], v[0:1]
	v_mov_b32_e32 v0, 0
	s_waitcnt lgkmcnt(0)
	s_barrier
	s_movk_i32 s12, 0x7400
	v_add3_u32 v222, s12, v208, v209
	ds_read_b128 v[142:145], v222 offset:4608
	ds_read_b128 v[146:149], v222 offset:4640
	ds_read_b128 v[150:153], v222 offset:4672
	ds_read_b128 v[154:157], v222 offset:4704
	s_setprio 1
	s_waitcnt lgkmcnt(3)
	v_mfma_f32_32x32x16_bf16 v[98:113], v[142:145], v[114:117], v[66:81]
	s_waitcnt lgkmcnt(2)
	v_mfma_f32_32x32x16_bf16 v[98:113], v[146:149], v[118:121], v[98:113]
	s_waitcnt lgkmcnt(1)
	v_mfma_f32_32x32x16_bf16 v[98:113], v[150:153], v[122:125], v[98:113]
	s_waitcnt lgkmcnt(0)
	v_mfma_f32_32x32x16_bf16 v[98:113], v[154:157], v[126:129], v[98:113]
	s_setprio 0
	s_nop 15
	v_max3_f32 v223, v98, v99, v100
	v_max3_f32 v224, v101, v102, v103
	v_max3_f32 v223, v223, v104, v105
	v_max3_f32 v224, v224, v106, v107
	v_max3_f32 v223, v223, v108, v109
	v_max3_f32 v224, v224, v110, v111
	v_max3_f32 v223, v223, v112, v113
	v_max_f32_e32 v223, v223, v224
	v_mov_b32_e32 v225, v223
	s_nop 1
	v_permlane32_swap_b32_e32 v223, v225
	v_max_f32_e32 v225, v223, v225
.Ld_loop:
	s_and_b32 s30, s29, 1
	s_mul_i32 s12, s30, 0x7400
	v_add3_u32 v222, s12, v208, v209
	v_add_u32_e32 v213, s12, v210
	v_add_u32_e32 v213, v213, v211
	s_cmp_eq_u32 s10, 0
	s_cselect_b64 s[16:17], -1, 0
	s_cmp_lg_u32 s10, 0
	s_cselect_b64 s[18:19], -1, 0
	s_waitcnt lgkmcnt(0)
	s_barrier
	ds_read_b128 v[142:145], v222 offset:0
	ds_read_b128 v[146:149], v222 offset:32
	ds_read_b128 v[150:153], v222 offset:64
	ds_read_b128 v[154:157], v222 offset:96
	ds_read_b64_tr_b16 v[226:227], v213 offset:9216
	ds_read_b64_tr_b16 v[230:231], v213 offset:9280
	ds_read_b64_tr_b16 v[234:235], v213 offset:9344
	ds_read_b64_tr_b16 v[238:239], v213 offset:9408
	ds_read_b64_tr_b16 v[228:229], v213 offset:11776
	ds_read_b64_tr_b16 v[232:233], v213 offset:11840
	ds_read_b64_tr_b16 v[236:237], v213 offset:11904
	ds_read_b64_tr_b16 v[240:241], v213 offset:11968
	v_cmp_lt_f32_e32 vcc, s61, v225
	s_or_b64 s[20:21], vcc, s[16:17]
	s_cmp_lg_u64 s[20:21], 0
	s_cbranch_scc1 .Ld_rareA
.Ld_goA:
	s_setprio 1
	s_waitcnt lgkmcnt(11)
	v_mfma_f32_32x32x16_bf16 v[82:97], v[142:145], v[114:117], v[66:81]
	v_exp_f32_e32 v98, v98
	v_exp_f32_e32 v99, v99
	s_waitcnt lgkmcnt(10)
	v_mfma_f32_32x32x16_bf16 v[82:97], v[146:149], v[118:121], v[82:97]
	v_exp_f32_e32 v100, v100
	v_exp_f32_e32 v101, v101
	v_cvt_pk_bf16_f32 v214, v98, v99
	s_waitcnt lgkmcnt(9)
	v_mfma_f32_32x32x16_bf16 v[82:97], v[150:153], v[122:125], v[82:97]
	v_exp_f32_e32 v102, v102
	v_exp_f32_e32 v103, v103
	v_cvt_pk_bf16_f32 v215, v100, v101
	s_waitcnt lgkmcnt(8)
	v_mfma_f32_32x32x16_bf16 v[82:97], v[154:157], v[126:129], v[82:97]
	v_exp_f32_e32 v104, v104
	v_exp_f32_e32 v105, v105
	v_cvt_pk_bf16_f32 v216, v102, v103
	v_cvt_pk_bf16_f32 v217, v104, v105
	ds_read_b64_tr_b16 v[142:143], v213 offset:14336
	ds_read_b64_tr_b16 v[146:147], v213 offset:14400
	ds_read_b64_tr_b16 v[150:151], v213 offset:14464
	ds_read_b64_tr_b16 v[154:155], v213 offset:14528
	ds_read_b64_tr_b16 v[144:145], v213 offset:16896
	ds_read_b64_tr_b16 v[148:149], v213 offset:16960
	ds_read_b64_tr_b16 v[152:153], v213 offset:17024
	ds_read_b64_tr_b16 v[156:157], v213 offset:17088
	s_waitcnt lgkmcnt(11)
	v_mfma_f32_32x32x16_bf16 v[50:65], v[226:229], v[214:217], v[50:65]
	v_exp_f32_e32 v106, v106
	v_exp_f32_e32 v107, v107
	v_add_f32_e32 v248, v98, v100
	s_waitcnt lgkmcnt(10)
	v_mfma_f32_32x32x16_bf16 v[34:49], v[230:233], v[214:217], v[34:49]
	v_exp_f32_e32 v108, v108
	v_exp_f32_e32 v109, v109
	v_cvt_pk_bf16_f32 v218, v106, v107
	v_add_f32_e32 v249, v99, v101
	s_waitcnt lgkmcnt(9)
	v_mfma_f32_32x32x16_bf16 v[18:33], v[234:237], v[214:217], v[18:33]
	v_exp_f32_e32 v110, v110
	v_exp_f32_e32 v111, v111
	v_cvt_pk_bf16_f32 v219, v108, v109
	v_add_f32_e32 v248, v248, v102
	s_waitcnt lgkmcnt(8)
	v_mfma_f32_32x32x16_bf16 v[2:17], v[238:241], v[214:217], v[2:17]
	v_exp_f32_e32 v112, v112
	v_exp_f32_e32 v113, v113
	v_cvt_pk_bf16_f32 v220, v110, v111
	v_cvt_pk_bf16_f32 v221, v112, v113
	ds_read_b128 v[226:229], v222 offset:4608
	ds_read_b128 v[230:233], v222 offset:4640
	ds_read_b128 v[234:237], v222 offset:4672
	ds_read_b128 v[238:241], v222 offset:4704
	s_waitcnt lgkmcnt(7)
	v_mfma_f32_32x32x16_bf16 v[50:65], v[142:145], v[218:221], v[50:65]
	v_add_f32_e32 v249, v249, v103
	v_add_f32_e32 v248, v248, v104
	v_add_f32_e32 v249, v249, v105
	v_max3_f32 v223, v82, v83, v84
	v_max3_f32 v224, v85, v86, v87
	s_waitcnt lgkmcnt(6)
	v_mfma_f32_32x32x16_bf16 v[34:49], v[146:149], v[218:221], v[34:49]
	v_add_f32_e32 v248, v248, v106
	v_add_f32_e32 v249, v249, v107
	v_add_f32_e32 v248, v248, v108
	v_max3_f32 v223, v223, v88, v89
	v_max3_f32 v224, v224, v90, v91
	s_waitcnt lgkmcnt(5)
	v_mfma_f32_32x32x16_bf16 v[18:33], v[150:153], v[218:221], v[18:33]
	v_add_f32_e32 v249, v249, v109
	v_add_f32_e32 v248, v248, v110
	v_add_f32_e32 v249, v249, v111
	v_max3_f32 v223, v223, v92, v93
	v_max3_f32 v224, v224, v94, v95
	s_waitcnt lgkmcnt(4)
	v_mfma_f32_32x32x16_bf16 v[2:17], v[154:157], v[218:221], v[2:17]
	s_setprio 0
	ds_read_b64_tr_b16 v[142:143], v213 offset:19456
	ds_read_b64_tr_b16 v[146:147], v213 offset:19520
	ds_read_b64_tr_b16 v[150:151], v213 offset:19584
	ds_read_b64_tr_b16 v[154:155], v213 offset:19648
	ds_read_b64_tr_b16 v[144:145], v213 offset:22016
	ds_read_b64_tr_b16 v[148:149], v213 offset:22080
	ds_read_b64_tr_b16 v[152:153], v213 offset:22144
	ds_read_b64_tr_b16 v[156:157], v213 offset:22208
	v_add_f32_e32 v248, v248, v112
	v_add_f32_e32 v249, v249, v113
	v_add_f32_e32 v248, v248, v249
	v_add_f32_e32 v0, v0, v248
	v_max3_f32 v223, v223, v96, v97
	v_max_f32_e32 v223, v223, v224
	v_mov_b32_e32 v225, v223
	s_nop 1
	v_permlane32_swap_b32_e32 v223, v225
	v_max_f32_e32 v225, v223, v225
	v_cmp_lt_f32_e32 vcc, s61, v225
	s_cmp_lg_u64 vcc, 0
	s_cbranch_scc1 .Ld_rareB
.Ld_goB:
	s_setprio 1
	s_waitcnt lgkmcnt(11)
	v_mfma_f32_32x32x16_bf16 v[98:113], v[226:229], v[114:117], v[66:81]
	v_exp_f32_e32 v82, v82
	v_exp_f32_e32 v83, v83
	s_waitcnt lgkmcnt(10)
	v_mfma_f32_32x32x16_bf16 v[98:113], v[230:233], v[118:121], v[98:113]
	v_exp_f32_e32 v84, v84
	v_exp_f32_e32 v85, v85
	v_cvt_pk_bf16_f32 v214, v82, v83
	s_waitcnt lgkmcnt(9)
	v_mfma_f32_32x32x16_bf16 v[98:113], v[234:237], v[122:125], v[98:113]
	v_exp_f32_e32 v86, v86
	v_exp_f32_e32 v87, v87
	v_cvt_pk_bf16_f32 v215, v84, v85
	s_waitcnt lgkmcnt(8)
	v_mfma_f32_32x32x16_bf16 v[98:113], v[238:241], v[126:129], v[98:113]
	v_exp_f32_e32 v88, v88
	v_exp_f32_e32 v89, v89
	v_cvt_pk_bf16_f32 v216, v86, v87
	v_cvt_pk_bf16_f32 v217, v88, v89
	ds_read_b64_tr_b16 v[226:227], v213 offset:24576
	ds_read_b64_tr_b16 v[230:231], v213 offset:24640
	ds_read_b64_tr_b16 v[234:235], v213 offset:24704
	ds_read_b64_tr_b16 v[238:239], v213 offset:24768
	ds_read_b64_tr_b16 v[228:229], v213 offset:27136
	ds_read_b64_tr_b16 v[232:233], v213 offset:27200
	ds_read_b64_tr_b16 v[236:237], v213 offset:27264
	ds_read_b64_tr_b16 v[240:241], v213 offset:27328
	s_waitcnt lgkmcnt(11)
	v_mfma_f32_32x32x16_bf16 v[50:65], v[142:145], v[214:217], v[50:65]
	v_exp_f32_e32 v90, v90
	v_exp_f32_e32 v91, v91
	v_add_f32_e32 v248, v82, v84
	s_waitcnt lgkmcnt(10)
	v_mfma_f32_32x32x16_bf16 v[34:49], v[146:149], v[214:217], v[34:49]
	v_exp_f32_e32 v92, v92
	v_exp_f32_e32 v93, v93
	v_cvt_pk_bf16_f32 v218, v90, v91
	v_add_f32_e32 v249, v83, v85
	s_waitcnt lgkmcnt(9)
	v_mfma_f32_32x32x16_bf16 v[18:33], v[150:153], v[214:217], v[18:33]
	v_exp_f32_e32 v94, v94
	v_exp_f32_e32 v95, v95
	v_cvt_pk_bf16_f32 v219, v92, v93
	v_add_f32_e32 v248, v248, v86
	s_waitcnt lgkmcnt(8)
	v_mfma_f32_32x32x16_bf16 v[2:17], v[154:157], v[214:217], v[2:17]
	v_exp_f32_e32 v96, v96
	v_exp_f32_e32 v97, v97
	v_cvt_pk_bf16_f32 v220, v94, v95
	v_cvt_pk_bf16_f32 v221, v96, v97
	s_waitcnt lgkmcnt(3)
	v_mfma_f32_32x32x16_bf16 v[50:65], v[226:229], v[218:221], v[50:65]
	v_add_f32_e32 v249, v249, v87
	v_add_f32_e32 v248, v248, v88
	v_add_f32_e32 v249, v249, v89
	v_max3_f32 v223, v98, v99, v100
	v_max3_f32 v224, v101, v102, v103
	s_waitcnt lgkmcnt(2)
	v_mfma_f32_32x32x16_bf16 v[34:49], v[230:233], v[218:221], v[34:49]
	v_add_f32_e32 v248, v248, v90
	v_add_f32_e32 v249, v249, v91
	v_add_f32_e32 v248, v248, v92
	v_max3_f32 v223, v223, v104, v105
	v_max3_f32 v224, v224, v106, v107
	s_waitcnt lgkmcnt(1)
	v_mfma_f32_32x32x16_bf16 v[18:33], v[234:237], v[218:221], v[18:33]
	v_add_f32_e32 v249, v249, v93
	v_add_f32_e32 v248, v248, v94
	v_add_f32_e32 v249, v249, v95
	v_max3_f32 v223, v223, v108, v109
	v_max3_f32 v224, v224, v110, v111
	s_waitcnt lgkmcnt(0)
	v_mfma_f32_32x32x16_bf16 v[2:17], v[238:241], v[218:221], v[2:17]
	s_setprio 0
	v_add_f32_e32 v248, v248, v96
	v_add_f32_e32 v249, v249, v97
	v_add_f32_e32 v248, v248, v249
	v_add_f32_e32 v0, v0, v248
	v_max3_f32 v223, v223, v112, v113
	v_max_f32_e32 v223, v223, v224
	v_mov_b32_e32 v225, v223
	s_nop 1
	v_permlane32_swap_b32_e32 v223, v225
	v_max_f32_e32 v225, v223, v225
	s_cmp_eq_u32 s10, 0x17a0000
	s_cbranch_scc1 .Ld_next
	s_xor_b32 s12, s30, 1
	s_mulk_i32 s12, 0x7400
	v_add3_u32 v246, s12, v206, v183
	s_waitcnt vmcnt(2)
	ds_write_b128 v246, v[130:133]
	v_add3_u32 v246, s12, v205, v207
	s_cmp_gt_u32 s29, 61
	s_waitcnt vmcnt(1)
	ds_write_b128 v246, v[134:137] offset:9216
	s_waitcnt vmcnt(0)
	ds_write_b128 v246, v[138:141] offset:19456
	s_cbranch_scc1 .Ld_next
	v_lshl_add_u64 v[130:131], v[188:189], 0, s[10:11]
	v_lshl_add_u64 v[134:135], v[190:191], 0, s[10:11]
	v_lshl_add_u64 v[138:139], v[192:193], 0, s[10:11]
	global_load_dwordx4 v[130:133], v[130:131], off
	s_nop 0
	global_load_dwordx4 v[134:137], v[134:135], off
	s_nop 0
	global_load_dwordx4 v[138:141], v[138:139], off
.Ld_next:
	s_add_u32 s10, s10, 0x60000
	s_addc_u32 s11, s11, 0
	s_add_i32 s29, s29, 1
	s_cmp_lg_u32 s10, 0x1800000
	s_cbranch_scc1 .Ld_loop
	s_branch .LBB0_811
.Ld_rareA:
	s_nop 15
	v_max_f32_e32 v66, v225, v225
	s_andn2_b64 vcc, exec, s[18:19]
	v_max_f32_e32 v66, 0, v66
	s_cbranch_vccnz .Ld_rareA2
	v_exp_f32_e64 v68, -v66
	s_nop 0
	v_mul_f32_e32 v0, v0, v68
	v_pk_mul_f32 v[64:65], v[64:65], v[68:69] op_sel_hi:[1,0]
	v_pk_mul_f32 v[62:63], v[62:63], v[68:69] op_sel_hi:[1,0]
	v_pk_mul_f32 v[60:61], v[60:61], v[68:69] op_sel_hi:[1,0]
	v_pk_mul_f32 v[58:59], v[58:59], v[68:69] op_sel_hi:[1,0]
	v_pk_mul_f32 v[56:57], v[56:57], v[68:69] op_sel_hi:[1,0]
	v_pk_mul_f32 v[54:55], v[54:55], v[68:69] op_sel_hi:[1,0]
	v_pk_mul_f32 v[52:53], v[52:53], v[68:69] op_sel_hi:[1,0]
	v_pk_mul_f32 v[50:51], v[50:51], v[68:69] op_sel_hi:[1,0]
	v_pk_mul_f32 v[48:49], v[48:49], v[68:69] op_sel_hi:[1,0]
	v_pk_mul_f32 v[46:47], v[46:47], v[68:69] op_sel_hi:[1,0]
	v_pk_mul_f32 v[44:45], v[44:45], v[68:69] op_sel_hi:[1,0]
	v_pk_mul_f32 v[42:43], v[42:43], v[68:69] op_sel_hi:[1,0]
	v_pk_mul_f32 v[40:41], v[40:41], v[68:69] op_sel_hi:[1,0]
	v_pk_mul_f32 v[38:39], v[38:39], v[68:69] op_sel_hi:[1,0]
	v_pk_mul_f32 v[36:37], v[36:37], v[68:69] op_sel_hi:[1,0]
	v_pk_mul_f32 v[34:35], v[34:35], v[68:69] op_sel_hi:[1,0]
	v_pk_mul_f32 v[32:33], v[32:33], v[68:69] op_sel_hi:[1,0]
	v_pk_mul_f32 v[30:31], v[30:31], v[68:69] op_sel_hi:[1,0]
	v_pk_mul_f32 v[28:29], v[28:29], v[68:69] op_sel_hi:[1,0]
	v_pk_mul_f32 v[26:27], v[26:27], v[68:69] op_sel_hi:[1,0]
	v_pk_mul_f32 v[24:25], v[24:25], v[68:69] op_sel_hi:[1,0]
	v_pk_mul_f32 v[22:23], v[22:23], v[68:69] op_sel_hi:[1,0]
	v_pk_mul_f32 v[20:21], v[20:21], v[68:69] op_sel_hi:[1,0]
	v_pk_mul_f32 v[18:19], v[18:19], v[68:69] op_sel_hi:[1,0]
	v_pk_mul_f32 v[16:17], v[16:17], v[68:69] op_sel_hi:[1,0]
	v_pk_mul_f32 v[14:15], v[14:15], v[68:69] op_sel_hi:[1,0]
	v_pk_mul_f32 v[12:13], v[12:13], v[68:69] op_sel_hi:[1,0]
	v_pk_mul_f32 v[10:11], v[10:11], v[68:69] op_sel_hi:[1,0]
	v_pk_mul_f32 v[8:9], v[8:9], v[68:69] op_sel_hi:[1,0]
	v_pk_mul_f32 v[6:7], v[6:7], v[68:69] op_sel_hi:[1,0]
	v_pk_mul_f32 v[4:5], v[4:5], v[68:69] op_sel_hi:[1,0]
	v_pk_mul_f32 v[2:3], v[2:3], v[68:69] op_sel_hi:[1,0]
.Ld_rareA2:
	v_cndmask_b32_e64 v66, v66, v225, s[16:17]
	v_add_f32_e32 v212, v212, v66
	v_xor_b32_e32 v81, 0x80000000, v212
	v_pk_add_f32 v[98:99], v[98:99], v[66:67] op_sel_hi:[1,0] neg_lo:[0,1] neg_hi:[0,1]
	v_pk_add_f32 v[100:101], v[100:101], v[66:67] op_sel_hi:[1,0] neg_lo:[0,1] neg_hi:[0,1]
	v_pk_add_f32 v[102:103], v[102:103], v[66:67] op_sel_hi:[1,0] neg_lo:[0,1] neg_hi:[0,1]
	v_pk_add_f32 v[104:105], v[104:105], v[66:67] op_sel_hi:[1,0] neg_lo:[0,1] neg_hi:[0,1]
	v_pk_add_f32 v[106:107], v[106:107], v[66:67] op_sel_hi:[1,0] neg_lo:[0,1] neg_hi:[0,1]
	v_pk_add_f32 v[108:109], v[108:109], v[66:67] op_sel_hi:[1,0] neg_lo:[0,1] neg_hi:[0,1]
	v_pk_add_f32 v[110:111], v[110:111], v[66:67] op_sel_hi:[1,0] neg_lo:[0,1] neg_hi:[0,1]
	v_pk_add_f32 v[112:113], v[112:113], v[66:67] op_sel_hi:[1,0] neg_lo:[0,1] neg_hi:[0,1]
	v_mov_b32_e32 v80, v81
	v_mov_b32_e32 v79, v81
	v_mov_b32_e32 v78, v81
	v_mov_b32_e32 v77, v81
	v_mov_b32_e32 v76, v81
	v_mov_b32_e32 v75, v81
	v_mov_b32_e32 v74, v81
	v_mov_b32_e32 v73, v81
	v_mov_b32_e32 v72, v81
	v_mov_b32_e32 v71, v81
	v_mov_b32_e32 v70, v81
	v_mov_b32_e32 v69, v81
	v_mov_b32_e32 v68, v81
	v_mov_b32_e32 v67, v81
	v_mov_b32_e32 v66, v81
	s_branch .Ld_goA
.Ld_rareB:
	s_nop 15
	v_max_f32_e32 v66, v225, v225
	v_max_f32_e32 v66, 0, v66
	v_exp_f32_e64 v68, -v66
	s_nop 0
	v_mul_f32_e32 v0, v0, v68
	v_pk_mul_f32 v[64:65], v[64:65], v[68:69] op_sel_hi:[1,0]
	v_pk_mul_f32 v[62:63], v[62:63], v[68:69] op_sel_hi:[1,0]
	v_pk_mul_f32 v[60:61], v[60:61], v[68:69] op_sel_hi:[1,0]
	v_pk_mul_f32 v[58:59], v[58:59], v[68:69] op_sel_hi:[1,0]
	v_pk_mul_f32 v[56:57], v[56:57], v[68:69] op_sel_hi:[1,0]
	v_pk_mul_f32 v[54:55], v[54:55], v[68:69] op_sel_hi:[1,0]
	v_pk_mul_f32 v[52:53], v[52:53], v[68:69] op_sel_hi:[1,0]
	v_pk_mul_f32 v[50:51], v[50:51], v[68:69] op_sel_hi:[1,0]
	v_pk_mul_f32 v[48:49], v[48:49], v[68:69] op_sel_hi:[1,0]
	v_pk_mul_f32 v[46:47], v[46:47], v[68:69] op_sel_hi:[1,0]
	v_pk_mul_f32 v[44:45], v[44:45], v[68:69] op_sel_hi:[1,0]
	v_pk_mul_f32 v[42:43], v[42:43], v[68:69] op_sel_hi:[1,0]
	v_pk_mul_f32 v[40:41], v[40:41], v[68:69] op_sel_hi:[1,0]
	v_pk_mul_f32 v[38:39], v[38:39], v[68:69] op_sel_hi:[1,0]
	v_pk_mul_f32 v[36:37], v[36:37], v[68:69] op_sel_hi:[1,0]
	v_pk_mul_f32 v[34:35], v[34:35], v[68:69] op_sel_hi:[1,0]
	v_pk_mul_f32 v[32:33], v[32:33], v[68:69] op_sel_hi:[1,0]
	v_pk_mul_f32 v[30:31], v[30:31], v[68:69] op_sel_hi:[1,0]
	v_pk_mul_f32 v[28:29], v[28:29], v[68:69] op_sel_hi:[1,0]
	v_pk_mul_f32 v[26:27], v[26:27], v[68:69] op_sel_hi:[1,0]
	v_pk_mul_f32 v[24:25], v[24:25], v[68:69] op_sel_hi:[1,0]
	v_pk_mul_f32 v[22:23], v[22:23], v[68:69] op_sel_hi:[1,0]
	v_pk_mul_f32 v[20:21], v[20:21], v[68:69] op_sel_hi:[1,0]
	v_pk_mul_f32 v[18:19], v[18:19], v[68:69] op_sel_hi:[1,0]
	v_pk_mul_f32 v[16:17], v[16:17], v[68:69] op_sel_hi:[1,0]
	v_pk_mul_f32 v[14:15], v[14:15], v[68:69] op_sel_hi:[1,0]
	v_pk_mul_f32 v[12:13], v[12:13], v[68:69] op_sel_hi:[1,0]
	v_pk_mul_f32 v[10:11], v[10:11], v[68:69] op_sel_hi:[1,0]
	v_pk_mul_f32 v[8:9], v[8:9], v[68:69] op_sel_hi:[1,0]
	v_pk_mul_f32 v[6:7], v[6:7], v[68:69] op_sel_hi:[1,0]
	v_pk_mul_f32 v[4:5], v[4:5], v[68:69] op_sel_hi:[1,0]
	v_pk_mul_f32 v[2:3], v[2:3], v[68:69] op_sel_hi:[1,0]
	v_add_f32_e32 v212, v212, v66
	v_xor_b32_e32 v81, 0x80000000, v212
	v_pk_add_f32 v[82:83], v[82:83], v[66:67] op_sel_hi:[1,0] neg_lo:[0,1] neg_hi:[0,1]
	v_pk_add_f32 v[84:85], v[84:85], v[66:67] op_sel_hi:[1,0] neg_lo:[0,1] neg_hi:[0,1]
	v_pk_add_f32 v[86:87], v[86:87], v[66:67] op_sel_hi:[1,0] neg_lo:[0,1] neg_hi:[0,1]
	v_pk_add_f32 v[88:89], v[88:89], v[66:67] op_sel_hi:[1,0] neg_lo:[0,1] neg_hi:[0,1]
	v_pk_add_f32 v[90:91], v[90:91], v[66:67] op_sel_hi:[1,0] neg_lo:[0,1] neg_hi:[0,1]
	v_pk_add_f32 v[92:93], v[92:93], v[66:67] op_sel_hi:[1,0] neg_lo:[0,1] neg_hi:[0,1]
	v_pk_add_f32 v[94:95], v[94:95], v[66:67] op_sel_hi:[1,0] neg_lo:[0,1] neg_hi:[0,1]
	v_pk_add_f32 v[96:97], v[96:97], v[66:67] op_sel_hi:[1,0] neg_lo:[0,1] neg_hi:[0,1]
	v_mov_b32_e32 v80, v81
	v_mov_b32_e32 v79, v81
	v_mov_b32_e32 v78, v81
	v_mov_b32_e32 v77, v81
	v_mov_b32_e32 v76, v81
	v_mov_b32_e32 v75, v81
	v_mov_b32_e32 v74, v81
	v_mov_b32_e32 v73, v81
	v_mov_b32_e32 v72, v81
	v_mov_b32_e32 v71, v81
	v_mov_b32_e32 v70, v81
	v_mov_b32_e32 v69, v81
	v_mov_b32_e32 v68, v81
	v_mov_b32_e32 v67, v81
	v_mov_b32_e32 v66, v81
	s_branch .Ld_goB

	.amdhsa_kernel _Z10fwd_kernel6Params
		.amdhsa_group_segment_fixed_size 0
		.amdhsa_private_segment_fixed_size 0
		.amdhsa_kernarg_size 440
		.amdhsa_user_sgpr_count 2
		.amdhsa_user_sgpr_dispatch_ptr 0
		.amdhsa_user_sgpr_queue_ptr 0
		.amdhsa_user_sgpr_kernarg_segment_ptr 1
		.amdhsa_user_sgpr_dispatch_id 0
		.amdhsa_user_sgpr_kernarg_preload_length 0
		.amdhsa_user_sgpr_kernarg_preload_offset 0
		.amdhsa_user_sgpr_private_segment_size 0
		.amdhsa_uses_dynamic_stack 0
		.amdhsa_enable_private_segment 0
		.amdhsa_system_sgpr_workgroup_id_x 1
		.amdhsa_system_sgpr_workgroup_id_y 0
		.amdhsa_system_sgpr_workgroup_id_z 0
		.amdhsa_system_sgpr_workgroup_info 0
		.amdhsa_system_vgpr_workitem_id 2
		.amdhsa_next_free_vgpr 256
		.amdhsa_next_free_sgpr 102
		.amdhsa_accum_offset 256
		.amdhsa_reserve_vcc 1
		.amdhsa_float_round_mode_32 0
		.amdhsa_float_round_mode_16_64 0
		.amdhsa_float_denorm_mode_32 3
		.amdhsa_float_denorm_mode_16_64 3
		.amdhsa_dx10_clamp 1
		.amdhsa_ieee_mode 1
		.amdhsa_fp16_overflow 0
		.amdhsa_tg_split 0
		.amdhsa_exception_fp_ieee_invalid_op 0
		.amdhsa_exception_fp_denorm_src 0
		.amdhsa_exception_fp_ieee_div_zero 0
		.amdhsa_exception_fp_ieee_overflow 0
		.amdhsa_exception_fp_ieee_underflow 0
		.amdhsa_exception_fp_ieee_inexact 0
		.amdhsa_exception_int_div_zero 0
	.end_amdhsa_kernel

amdhsa.kernels:
  - .agpr_count:     0
    .args:
      - .offset:         0
        .size:           184
        .value_kind:     by_value
      - .offset:         184
        .size:           4
        .value_kind:     hidden_block_count_x
      - .offset:         188
        .size:           4
        .value_kind:     hidden_block_count_y
      - .offset:         192
        .size:           4
        .value_kind:     hidden_block_count_z
      - .offset:         196
        .size:           2
        .value_kind:     hidden_group_size_x
      - .offset:         198
        .size:           2
        .value_kind:     hidden_group_size_y
      - .offset:         200
        .size:           2
        .value_kind:     hidden_group_size_z
      - .offset:         202
        .size:           2
        .value_kind:     hidden_remainder_x
      - .offset:         204
        .size:           2
        .value_kind:     hidden_remainder_y
      - .offset:         206
        .size:           2
        .value_kind:     hidden_remainder_z
      - .offset:         224
        .size:           8
        .value_kind:     hidden_global_offset_x
      - .offset:         232
        .size:           8
        .value_kind:     hidden_global_offset_y
      - .offset:         240
        .size:           8
        .value_kind:     hidden_global_offset_z
      - .offset:         248
        .size:           2
        .value_kind:     hidden_grid_dims
      - .offset:         272
        .size:           8
        .value_kind:     hidden_multigrid_sync_arg
      - .offset:         304
        .size:           4
        .value_kind:     hidden_dynamic_lds_size
    .group_segment_fixed_size: 0
    .kernarg_segment_align: 8
    .kernarg_segment_size: 440
    .language:       OpenCL C
    .language_version:
      - 2
      - 0
    .max_flat_workgroup_size: 512
    .name:           _Z10fwd_kernel6Params
    .private_segment_fixed_size: 0
    .sgpr_count:     108
    .sgpr_spill_count: 102
    .symbol:         _Z10fwd_kernel6Params.kd
    .uniform_work_group_size: 1
    .uses_dynamic_stack: false
    .vgpr_count:     256
    .vgpr_spill_count: 0
    .wavefront_size: 64
